# HGRN state tiles stored in MFMA-fragment order (full-line stores/loads in stage1/scan/stage3) + scan loads ahead + layer-1 out epilogue full-line
# speedup vs baseline: 1.0652x; 1.0201x over previous
; #define LAS __attribute__((address_space(3)))
; __device__ __forceinline__ unsigned pk2(float lo, float hi) { f32x2_t v = {lo, hi}; bf16x2_t b = __builtin_convertvector(v, bf16x2_t); return __builtin_bit_cast(unsigned, b); }
; __device__ __forceinline__ float fexp(float x) { return __builtin_amdgcn_exp2f(x * LOG2E); }
; __device__ __forceinline__ void hgrn_stage1_unit(const Args& a, int l, LAS unsigned char* lds, int tid, int u, const HIn& in, HIn& nxt, int unext) {
;     const int lane = tid & 63, w = __builtin_amdgcn_readfirstlane(tid >> 6), fr = lane & 15, fq = lane >> 4;
;     const int bh = u >> 5, c = u & 31, hh = bh & 3;
;     LAS float* LF = (LAS float*)lds;
;     LAS unsigned char* KN = lds + 34816;
;     LAS unsigned char* VN = lds + 34816 + 18432;
;     float kf[16];
;     hgrn_stepA(a, l, lds, tid, hh, in, kf);
;     hgrn_load<false>(a, tid, unext, nxt);
;     hgrn_cumsum_scan(lds, tid);
;     if (tid < 128) ((float*)(a.ws + WS_DECAY))[((size_t)bh * 32 + c) * 128 + tid] = fexp(LF[63 * 128 + tid]);
; #pragma unroll
;     for (int ii = 0; ii < 2; ++ii) {
;         const int cid = tid + 512 * ii, t = cid >> 4, d0 = (cid & 15) * 8;
;         const f32x4 ae0 = *(const LAS f32x4*)(LF + 63 * 128 + d0), ae1 = *(const LAS f32x4*)(LF + 63 * 128 + d0 + 4), at0 = *(const LAS f32x4*)(LF + t * 128 + d0), at1 = *(const LAS f32x4*)(LF + t * 128 + d0 + 4);
;         const f32x4 e0 = ae0 - at0, e1 = ae1 - at1;
;         u32x4 o; o.x = pk2(kf[ii * 8 + 0] * fexp(e0.x), kf[ii * 8 + 1] * fexp(e0.y)); o.y = pk2(kf[ii * 8 + 2] * fexp(e0.z), kf[ii * 8 + 3] * fexp(e0.w));
;         o.z = pk2(kf[ii * 8 + 4] * fexp(e1.x), kf[ii * 8 + 5] * fexp(e1.y)); o.w = pk2(kf[ii * 8 + 6] * fexp(e1.z), kf[ii * 8 + 7] * fexp(e1.w));
;         *(LAS u32x4*)(KN + t * 288 + d0 * 2) = o;
;         *(LAS u32x4*)(VN + t * 288 + d0 * 2) = in.v[ii];
;     }
.LBB0_435:
	v_readlane_b32 s4, v244, 37
	v_readlane_b32 s5, v244, 38
	s_andn2_b64 vcc, exec, s[4:5]
	s_cbranch_vccnz .LBB0_448
	v_lshlrev_b32_e32 v0, 3, v96
	v_and_b32_e32 v16, 0x78, v0
	v_add_u32_e32 v0, 0x200, v96
	v_ashrrev_i32_e32 v34, 4, v0
	v_readlane_b32 s4, v244, 39
	v_ashrrev_i32_e32 v35, 31, v34
	v_readlane_b32 s5, v244, 40
	v_readlane_b32 s8, v244, 42
	v_readlane_b32 s9, v244, 43
	v_lshl_add_u64 v[0:1], s[4:5], 0, v[34:35]
	v_lshlrev_b64 v[0:1], 13, v[0:1]
	v_lshl_add_u64 v[0:1], s[8:9], 0, v[0:1]
	v_lshlrev_b32_e32 v144, 1, v16
	v_lshl_add_u64 v[0:1], v[0:1], 0, v[144:145]
	v_ashrrev_i32_e32 v32, 4, v96
	v_add_co_u32_e32 v4, vcc, s26, v0
	v_ashrrev_i32_e32 v33, 31, v32
	s_nop 0
	v_addc_co_u32_e32 v5, vcc, 0, v1, vcc
	global_load_dwordx4 v[0:3], v[4:5], off offset:3072
	global_load_dwordx4 v[8:11], v[4:5], off offset:2048
	v_lshl_add_u64 v[4:5], s[4:5], 0, v[32:33]
	v_lshlrev_b64 v[4:5], 13, v[4:5]
	v_lshl_add_u64 v[4:5], s[8:9], 0, v[4:5]
	v_lshl_add_u64 v[4:5], v[4:5], 0, v[144:145]
	v_add_co_u32_e32 v12, vcc, s26, v4
	s_add_i32 s4, 0, 0x1a000
	s_nop 0
	v_addc_co_u32_e32 v13, vcc, 0, v5, vcc
	global_load_dwordx4 v[4:7], v[12:13], off offset:3072
	s_nop 0
	global_load_dwordx4 v[12:15], v[12:13], off offset:2048
	v_lshlrev_b32_e32 v17, 2, v16
	v_add_u32_e32 v64, s4, v17
	v_add_u32_e32 v65, 0, v17
	v_and_b32_e32 v17, 0xfffffe00, v124
	v_add_u32_e32 v66, v65, v17
	v_and_b32_e32 v17, 0x7f, v96
	v_ashrrev_i32_e32 v18, 7, v96
	v_lshl_add_u32 v67, v17, 2, 0
	v_and_b32_e32 v17, 15, v96
	v_lshl_add_u32 v68, v18, 13, v67
	v_cmp_lt_i32_e64 s[44:45], 0, v18
	v_cmp_lt_i32_e64 s[46:47], 1, v18
	v_cmp_lt_i32_e64 s[48:49], 2, v18
	v_lshrrev_b32_e32 v18, 2, v96
	v_lshlrev_b32_e32 v24, 3, v17
	v_bfe_u32 v25, v96, 2, 4
	v_sub_u32_e32 v19, v65, v144
	v_lshlrev_b32_e32 v20, 9, v32
	v_mul_lo_u32 v21, v32, s27
	v_lshlrev_b32_e32 v22, 9, v34
	v_mul_lo_u32 v23, v34, s27
	v_and_b32_e32 v18, 12, v18
	v_and_b32_e32 v69, 24, v24
	v_mul_u32_u24_e32 v71, 0x120, v25
	v_mad_u32_u24 v72, v25, s27, 0
	v_or_b32_e32 v25, 0x60, v24
	v_or_b32_e32 v24, 0xe0, v24
	v_add_u32_e32 v70, 0, v69
	v_lshlrev_b32_e32 v73, 3, v17
	v_lshlrev_b32_e32 v144, 1, v16
	v_add_u32_e32 v74, v65, v20
	v_add_u32_e32 v75, v19, v21
	v_add_u32_e32 v76, v65, v22
	v_add_u32_e32 v77, v19, v23
	v_add_u32_e32 v78, v72, v25
	v_add_u32_e32 v79, v72, v24
	v_and_b32_e32 v36, 4, v18
	v_and_b32_e32 v25, 8, v18
	v_lshlrev_b32_e32 v36, 1, v36
	v_lshl_or_b32 v36, v25, 5, v36
	v_readlane_b32 s8, v244, 41
	s_branch .LBB0_438
.LBB0_437:
	s_or_b64 exec, exec, s[14:15]
	v_pk_add_f32 v[92:93], v[58:59], 1.0 op_sel_hi:[1,0] neg_lo:[1,0] neg_hi:[1,0]
	v_pk_add_f32 v[94:95], v[56:57], 1.0 op_sel_hi:[1,0] neg_lo:[1,0] neg_hi:[1,0]
	ds_read_b128 v[56:59], v65 offset:32256
	ds_read_b128 v[80:83], v65 offset:32272
	ds_read_b128 v[84:87], v74
	ds_read_b128 v[88:91], v74 offset:16
	v_pk_add_f32 v[26:27], v[26:27], 1.0 op_sel_hi:[1,0] neg_lo:[1,0] neg_hi:[1,0]
	v_pk_add_f32 v[30:31], v[30:31], 1.0 op_sel_hi:[1,0] neg_lo:[1,0] neg_hi:[1,0]
	v_pk_mul_f32 v[24:25], v[26:27], v[24:25]
	s_waitcnt lgkmcnt(1)
	v_sub_f32_e32 v57, v57, v85
	v_sub_f32_e32 v56, v56, v84
	v_mul_f32_e32 v56, 0x3fb8aa3b, v56
	v_mul_f32_e32 v57, 0x3fb8aa3b, v57
	v_exp_f32_e32 v56, v56
	v_exp_f32_e32 v57, v57
	v_sub_f32_e32 v58, v58, v86
	v_sub_f32_e32 v37, v59, v87
	v_pk_mul_f32 v[28:29], v[30:31], v[28:29]
	v_pk_mul_f32 v[24:25], v[24:25], v[56:57]
	s_waitcnt lgkmcnt(0)
	v_sub_f32_e32 v81, v81, v89
	v_cvt_pk_bf16_f32 v24, v24, v25
	v_mul_f32_e32 v25, 0x3fb8aa3b, v58
	v_exp_f32_e32 v26, v25
	v_mul_f32_e32 v25, 0x3fb8aa3b, v37
	v_exp_f32_e32 v27, v25
	v_sub_f32_e32 v80, v80, v88
	v_pk_add_f32 v[40:41], v[40:41], 1.0 op_sel_hi:[1,0] neg_lo:[1,0] neg_hi:[1,0]
	v_sub_f32_e32 v82, v82, v90
	v_pk_mul_f32 v[26:27], v[28:29], v[26:27]
	v_pk_mul_f32 v[28:29], v[40:41], v[38:39]
	v_cvt_pk_bf16_f32 v25, v26, v27
	v_mul_f32_e32 v26, 0x3fb8aa3b, v80
	v_mul_f32_e32 v27, 0x3fb8aa3b, v81
	v_exp_f32_e32 v26, v26
	v_exp_f32_e32 v27, v27
	v_sub_f32_e32 v59, v83, v91
	v_pk_add_f32 v[46:47], v[46:47], 1.0 op_sel_hi:[1,0] neg_lo:[1,0] neg_hi:[1,0]
	v_pk_add_f32 v[50:51], v[50:51], 1.0 op_sel_hi:[1,0] neg_lo:[1,0] neg_hi:[1,0]
	v_pk_mul_f32 v[26:27], v[28:29], v[26:27]
	v_pk_mul_f32 v[30:31], v[46:47], v[42:43]
	v_cvt_pk_bf16_f32 v26, v26, v27
	v_mul_f32_e32 v27, 0x3fb8aa3b, v82
	v_exp_f32_e32 v28, v27
	v_mul_f32_e32 v27, 0x3fb8aa3b, v59
	v_exp_f32_e32 v29, v27
	v_pk_add_f32 v[62:63], v[62:63], 1.0 op_sel_hi:[1,0] neg_lo:[1,0] neg_hi:[1,0]
	s_ashr_i32 s5, s5, 6
	s_lshl_b32 s8, s5, 5
	v_pk_mul_f32 v[28:29], v[30:31], v[28:29]
	v_add_u32_e32 v37, v72, v69
	v_cvt_pk_bf16_f32 v27, v28, v29
	ds_write_b128 v75, v[24:27] offset:34816
	ds_write_b128 v75, v[4:7] offset:53248
	ds_read_b128 v[4:7], v65 offset:32256
	ds_read_b128 v[24:27], v65 offset:32272
	ds_read_b128 v[28:31], v76
	ds_read_b128 v[38:41], v76 offset:16
	s_lshl_b32 s6, s6, 15
	s_andn2_b64 vcc, exec, s[52:53]
	s_waitcnt lgkmcnt(1)
	v_sub_f32_e32 v5, v5, v29
	v_sub_f32_e32 v4, v4, v28
	v_mul_f32_e32 v4, 0x3fb8aa3b, v4
	v_mul_f32_e32 v5, 0x3fb8aa3b, v5
	v_exp_f32_e32 v4, v4
	v_exp_f32_e32 v5, v5
	v_sub_f32_e32 v31, v7, v31
	v_sub_f32_e32 v30, v6, v30
	v_pk_mul_f32 v[6:7], v[50:51], v[44:45]
	s_waitcnt lgkmcnt(0)
	v_sub_f32_e32 v28, v25, v39
	v_pk_mul_f32 v[4:5], v[6:7], v[4:5]
	v_sub_f32_e32 v29, v24, v38
	v_cvt_pk_bf16_f32 v4, v4, v5
	v_mul_f32_e32 v5, 0x3fb8aa3b, v30
	v_exp_f32_e32 v6, v5
	v_mul_f32_e32 v5, 0x3fb8aa3b, v31
	v_exp_f32_e32 v7, v5
	v_pk_mul_f32 v[24:25], v[94:95], v[48:49]
	v_sub_f32_e32 v26, v26, v40
	v_sub_f32_e32 v27, v27, v41
	v_pk_mul_f32 v[6:7], v[24:25], v[6:7]
	v_pk_mul_f32 v[24:25], v[92:93], v[52:53]
	v_cvt_pk_bf16_f32 v5, v6, v7
	v_mul_f32_e32 v6, 0x3fb8aa3b, v29
	v_mul_f32_e32 v7, 0x3fb8aa3b, v28
	v_exp_f32_e32 v6, v6
	v_exp_f32_e32 v7, v7
	v_add3_u32 v28, v70, s8, v71
	v_add_u32_e32 v29, 0xd000, v28
	s_mov_b32 s8, s4
	v_pk_mul_f32 v[6:7], v[24:25], v[6:7]
	s_nop 0
	v_cvt_pk_bf16_f32 v6, v6, v7
	v_mul_f32_e32 v7, 0x3fb8aa3b, v26
	v_exp_f32_e32 v24, v7
	v_mul_f32_e32 v7, 0x3fb8aa3b, v27
	v_exp_f32_e32 v25, v7
	v_pk_mul_f32 v[26:27], v[62:63], v[54:55]
	s_nop 0
	v_pk_mul_f32 v[24:25], v[26:27], v[24:25]
	s_nop 0
	v_cvt_pk_bf16_f32 v7, v24, v25
	ds_write_b128 v77, v[4:7] offset:34816
	ds_write_b128 v77, v[0:3] offset:53248
	s_waitcnt lgkmcnt(0)
	s_barrier
; __device__ __forceinline__ unsigned pk2(float lo, float hi) { f32x2_t v = {lo, hi}; bf16x2_t b = __builtin_convertvector(v, bf16x2_t); return __builtin_bit_cast(unsigned, b); }
; #define MFMA16(a, b, c) __builtin_amdgcn_mfma_f32_16x16x32_bf16((a), (b), (c), 0, 0, 0)
; #define BAR_LDS() do { asm volatile("s_waitcnt lgkmcnt(0)" ::: "memory"); __builtin_amdgcn_s_barrier(); asm volatile("" ::: "memory"); } while (0)
; __device__ __forceinline__ void hgrn_stage1_unit(const Args& a, int l, LAS unsigned char* lds, int tid, int u, const HIn& in, HIn& nxt, int unext) {
;     ...
;     f32x4 acc[8];
; #pragma unroll
;     for (int n = 0; n < 8; ++n) acc[n] = (f32x4){0.f, 0.f, 0.f, 0.f};
; #pragma unroll
;     for (int ks = 0; ks < 2; ++ks) {
;         const s16x4 alo = tr4(VN, 288, ks * 32 + fq * 4, w * 16, fr), ahi = tr4(VN, 288, ks * 32 + 16 + fq * 4, w * 16, fr);
;         const bf16x8 af = __builtin_shufflevector(alo, ahi, 0, 1, 2, 3, 4, 5, 6, 7);
; #pragma unroll
;         for (int n = 0; n < 8; ++n) { const s16x4 blo = tr4(KN, 288, ks * 32 + fq * 4, n * 16, fr), bhi = tr4(KN, 288, ks * 32 + 16 + fq * 4, n * 16, fr);
;             const bf16x8 bfr = __builtin_shufflevector(blo, bhi, 0, 1, 2, 3, 4, 5, 6, 7); acc[n] = MFMA16(bfr, af, acc[n]); }
;     }
;     bf16_t* ST = (bf16_t*)(a.ws + WS_H) + ((size_t)bh * 32 + c) * 16384;
; #pragma unroll
;     for (int n = 0; n < 8; ++n) { u32x2 o; o.x = pk2(acc[n][0], acc[n][1]); o.y = pk2(acc[n][2], acc[n][3]); *(u32x2*)(ST + (w * 16 + fr) * 128 + n * 16 + fq * 4) = o; }
;     BAR_LDS();
	ds_read_b64_tr_b16 v[0:1], v28 offset:53248
	ds_read_b64_tr_b16 v[2:3], v28 offset:57856
	ds_read_b64_tr_b16 v[6:7], v37 offset:39424
	ds_read_b64_tr_b16 v[4:5], v37 offset:34816
	ds_read_b64_tr_b16 v[24:25], v37 offset:34848
	ds_read_b64_tr_b16 v[26:27], v37 offset:39456
	s_waitcnt lgkmcnt(0)
	v_mfma_f32_16x16x32_bf16 v[38:41], v[24:27], v[0:3], 0
	ds_read_b64_tr_b16 v[24:25], v37 offset:34880
	ds_read_b64_tr_b16 v[26:27], v37 offset:39488
	s_waitcnt lgkmcnt(0)
	v_mfma_f32_16x16x32_bf16 v[42:45], v[24:27], v[0:3], 0
	ds_read_b64_tr_b16 v[24:25], v78 offset:34816
	ds_read_b64_tr_b16 v[26:27], v78 offset:39424
	s_waitcnt lgkmcnt(0)
	v_mfma_f32_16x16x32_bf16 v[46:49], v[24:27], v[0:3], 0
	ds_read_b64_tr_b16 v[24:25], v37 offset:34944
	ds_read_b64_tr_b16 v[26:27], v37 offset:39552
	s_waitcnt lgkmcnt(0)
	v_mfma_f32_16x16x32_bf16 v[50:53], v[24:27], v[0:3], 0
	ds_read_b64_tr_b16 v[24:25], v37 offset:34976
	ds_read_b64_tr_b16 v[26:27], v37 offset:39584
	s_waitcnt lgkmcnt(0)
	v_mfma_f32_16x16x32_bf16 v[54:57], v[24:27], v[0:3], 0
	ds_read_b64_tr_b16 v[24:25], v37 offset:35008
	ds_read_b64_tr_b16 v[26:27], v37 offset:39616
	s_waitcnt lgkmcnt(0)
	v_mfma_f32_16x16x32_bf16 v[80:83], v[24:27], v[0:3], 0
	ds_read_b64_tr_b16 v[24:25], v79 offset:34816
	ds_read_b64_tr_b16 v[26:27], v79 offset:39424
	v_mfma_f32_16x16x32_bf16 v[4:7], v[4:7], v[0:3], 0
	s_waitcnt lgkmcnt(0)
	v_mfma_f32_16x16x32_bf16 v[24:27], v[24:27], v[0:3], 0
	ds_read_b64_tr_b16 v[84:85], v28 offset:62464
	ds_read_b64_tr_b16 v[86:87], v29 offset:13824
	ds_read_b64_tr_b16 v[0:1], v37 offset:44032
	ds_read_b64_tr_b16 v[2:3], v37 offset:48640
	s_waitcnt lgkmcnt(0)
	v_mfma_f32_16x16x32_bf16 v[28:31], v[0:3], v[84:87], v[4:7]
	ds_read_b64_tr_b16 v[0:1], v37 offset:44064
	ds_read_b64_tr_b16 v[2:3], v37 offset:48672
	s_waitcnt lgkmcnt(0)
	v_mfma_f32_16x16x32_bf16 v[4:7], v[0:3], v[84:87], v[38:41]
	ds_read_b64_tr_b16 v[0:1], v37 offset:44096
	ds_read_b64_tr_b16 v[2:3], v37 offset:48704
	s_nop 0
	ds_read_b64_tr_b16 v[38:39], v78 offset:44032
	ds_read_b64_tr_b16 v[40:41], v78 offset:48640
	v_cvt_pk_bf16_f32 v28, v28, v29
	s_waitcnt lgkmcnt(2)
	v_mfma_f32_16x16x32_bf16 v[0:3], v[0:3], v[84:87], v[42:45]
	s_nop 2
	ds_read_b64_tr_b16 v[42:43], v37 offset:44160
	ds_read_b64_tr_b16 v[44:45], v37 offset:48768
	v_cvt_pk_bf16_f32 v29, v30, v31
	v_cvt_pk_bf16_f32 v4, v4, v5
	s_waitcnt lgkmcnt(2)
	v_mfma_f32_16x16x32_bf16 v[38:41], v[38:41], v[84:87], v[46:49]
	s_nop 2
	ds_read_b64_tr_b16 v[46:47], v37 offset:44192
	ds_read_b64_tr_b16 v[48:49], v37 offset:48800
	v_cvt_pk_bf16_f32 v0, v0, v1
	v_cvt_pk_bf16_f32 v1, v2, v3
	s_waitcnt lgkmcnt(2)
	v_mfma_f32_16x16x32_bf16 v[42:45], v[42:45], v[84:87], v[50:53]
	s_nop 2
	ds_read_b64_tr_b16 v[50:51], v37 offset:44224
	ds_read_b64_tr_b16 v[52:53], v37 offset:48832
	v_mov_b32_e32 v37, v145
	v_cvt_pk_bf16_f32 v5, v6, v7
	s_waitcnt lgkmcnt(2)
	v_mfma_f32_16x16x32_bf16 v[46:49], v[46:49], v[84:87], v[54:57]
	s_nop 2
	ds_read_b64_tr_b16 v[54:55], v79 offset:44032
	ds_read_b64_tr_b16 v[56:57], v79 offset:48640
	s_waitcnt lgkmcnt(0)
	v_mfma_f32_16x16x32_bf16 v[24:27], v[54:57], v[84:87], v[24:27]
	v_lshlrev_b64 v[54:55], 20, v[60:61]
	v_lshl_add_u64 v[54:55], s[88:89], 0, v[54:55]
	v_lshl_or_b32 v56, s5, 11, v73
	v_lshl_add_u64 v[54:55], v[54:55], 0, s[6:7]
	v_ashrrev_i32_e32 v57, 31, v56
	v_lshl_add_u64 v[54:55], v[56:57], 1, v[54:55]
	v_mfma_f32_16x16x32_bf16 v[50:53], v[50:53], v[84:87], v[80:83]
	v_lshl_add_u64 v[54:55], v[54:55], 0, v[36:37]
	global_store_dwordx2 v[54:55], v[0:1], off offset:1024
	v_cvt_pk_bf16_f32 v0, v38, v39
	v_cvt_pk_bf16_f32 v1, v40, v41
	global_store_dwordx2 v[54:55], v[0:1], off offset:1536
	v_cvt_pk_bf16_f32 v0, v42, v43
	v_cvt_pk_bf16_f32 v1, v44, v45
	global_store_dwordx2 v[54:55], v[0:1], off offset:2048
	v_cvt_pk_bf16_f32 v0, v46, v47
	v_cvt_pk_bf16_f32 v1, v48, v49
	global_store_dwordx2 v[54:55], v[0:1], off offset:2560
	v_cvt_pk_bf16_f32 v0, v50, v51
	v_cvt_pk_bf16_f32 v1, v52, v53
	global_store_dwordx2 v[54:55], v[0:1], off offset:3072
	v_cvt_pk_bf16_f32 v0, v24, v25
	v_cvt_pk_bf16_f32 v1, v26, v27
	global_store_dwordx2 v[54:55], v[28:29], off
	global_store_dwordx2 v[54:55], v[4:5], off offset:512
	global_store_dwordx2 v[54:55], v[0:1], off offset:3584
	s_waitcnt lgkmcnt(0)
	s_barrier
	s_waitcnt vmcnt(8)
	v_mov_b64_e32 v[0:1], v[20:21]
	v_mov_b64_e32 v[4:5], v[16:17]
	v_mov_b64_e32 v[2:3], v[22:23]
	v_mov_b64_e32 v[6:7], v[18:19]
	s_cbranch_vccz .LBB0_448

; #define LAS __attribute__((address_space(3)))
; __device__ __forceinline__ float bflo(unsigned u) { return __uint_as_float(u << 16); }
; __device__ __forceinline__ float bfhi(unsigned u) { return __uint_as_float(u & 0xffff0000u); }
; __device__ __forceinline__ float sigm(float x) { return frcp(1.f + fexp(-x)); }
; __device__ __forceinline__ void hgrn_stepA(const Args& a, int l, LAS unsigned char* lds, int tid, int hh, const HIn& in, float (&kf)[16]) {
;     LAS float* LF = (LAS float*)lds;
;     LAS float* PT = (LAS float*)(lds + 32768);
; #pragma unroll
;     for (int ii = 0; ii < 2; ++ii) {
;         const int cid = tid + 512 * ii, t = cid >> 4, d0 = (cid & 15) * 8;
;         const u32x4 u = in.f[ii];
;         float fl[8] = {bflo(u.x), bfhi(u.x), bflo(u.y), bfhi(u.y), bflo(u.z), bfhi(u.z), bflo(u.w), bfhi(u.w)};
;         float lf[8];
;         const LAS float* LB = (const LAS float*)(lds + 106496) + hh * 128 + d0; const f32x4 lb0 = *(const LAS f32x4*)LB, lb1 = *(const LAS f32x4*)(LB + 4);
;         const float lbv[8] = {lb0.x, lb0.y, lb0.z, lb0.w, lb1.x, lb1.y, lb1.z, lb1.w};
; #pragma unroll
;         for (int i = 0; i < 8; ++i) { const float lb = lbv[i]; const float sg = sigm(fl[i]);
;             const float f = lb + (1.f - lb) * sg; lf[i] = __logf(f); kf[ii * 8 + i] = (1.f - lb) * (1.f - sg); }
;         *(LAS f32x4*)(LF + t * 128 + d0) = (f32x4){lf[0], lf[1], lf[2], lf[3]}; *(LAS f32x4*)(LF + t * 128 + d0 + 4) = (f32x4){lf[4], lf[5], lf[6], lf[7]};
;     }
.LBB0_644:
	s_mov_b32 s4, s8
	s_add_i32 s8, s8, s3
	s_waitcnt vmcnt(0)
	v_lshlrev_b32_e32 v13, 16, v4
	s_cmpk_gt_i32 s8, 0x3ff
	v_mul_f32_e32 v13, 0xbfb8aa3b, v13
	s_cselect_b64 s[70:71], -1, 0
	s_cmpk_lt_i32 s8, 0x400
	v_exp_f32_e32 v13, v13
	s_cselect_b32 s5, s8, s4
	s_ashr_i32 s60, s4, 5
	s_and_b32 s9, s60, 3
	v_lshl_add_u32 v12, s9, 9, v170
	v_and_b32_e32 v14, 0xffff0000, v4
	v_lshlrev_b32_e32 v15, 16, v5
	v_and_b32_e32 v16, 0xffff0000, v5
	v_lshlrev_b32_e32 v17, 16, v6
	v_and_b32_e32 v18, 0xffff0000, v6
	v_lshlrev_b32_e32 v19, 16, v7
	v_and_b32_e32 v20, 0xffff0000, v7
	ds_read_b128 v[8:11], v12
	ds_read_b128 v[4:7], v12 offset:16
	v_add_f32_e32 v13, 1.0, v13
	v_rcp_f32_e32 v104, v13
	v_mul_f32_e32 v13, 0xbfb8aa3b, v14
	v_exp_f32_e32 v13, v13
	s_waitcnt lgkmcnt(1)
	v_pk_add_f32 v[106:107], v[8:9], 1.0 op_sel_hi:[1,0] neg_lo:[1,0] neg_hi:[1,0]
	v_pk_add_f32 v[110:111], v[10:11], 1.0 op_sel_hi:[1,0] neg_lo:[1,0] neg_hi:[1,0]
	v_fma_f32 v8, v104, v106, v8
	v_add_f32_e32 v13, 1.0, v13
	v_cmp_gt_f32_e32 vcc, s28, v8
	v_rcp_f32_e32 v105, v13
	s_waitcnt lgkmcnt(0)
	v_pk_add_f32 v[114:115], v[4:5], 1.0 op_sel_hi:[1,0] neg_lo:[1,0] neg_hi:[1,0]
	v_cndmask_b32_e64 v13, 0, 32, vcc
	v_ldexp_f32 v8, v8, v13
	v_log_f32_e32 v8, v8
	v_fma_f32 v9, v105, v107, v9
	v_pk_add_f32 v[138:139], v[6:7], 1.0 op_sel_hi:[1,0] neg_lo:[1,0] neg_hi:[1,0]
	v_and_b32_e32 v14, 0xffff0000, v2
	v_mul_f32_e32 v13, 0x3f317217, v8
	v_fma_f32 v13, v8, s29, -v13
	v_fmac_f32_e32 v13, 0x3377d1cf, v8
	v_fmac_f32_e32 v13, 0x3f317217, v8
	v_cmp_lt_f32_e64 s[58:59], |v8|, s30
	v_readfirstlane_b32 s10, v121
	s_and_b32 s14, s4, 31
	v_cndmask_b32_e64 v8, v8, v13, s[58:59]
	v_cndmask_b32_e32 v13, 0, v190, vcc
	v_cmp_gt_f32_e32 vcc, s28, v9
	v_sub_f32_e32 v8, v8, v13
	s_ashr_i32 s40, s4, 7
	v_cndmask_b32_e64 v13, 0, 32, vcc
	v_ldexp_f32 v9, v9, v13
	v_log_f32_e32 v9, v9
	s_bfe_u32 s11, s10, 0x20006
	s_ashr_i32 s61, s60, 31
	s_ashr_i32 s41, s40, 31
	v_mul_f32_e32 v13, 0x3f317217, v9
	v_fma_f32 v13, v9, s29, -v13
	v_fmac_f32_e32 v13, 0x3377d1cf, v9
	v_fmac_f32_e32 v13, 0x3f317217, v9
	v_cmp_lt_f32_e64 s[58:59], |v9|, s30
	s_lshl_b32 s6, s14, 6
	s_ashr_i32 s36, s10, 8
	v_cndmask_b32_e64 v9, v9, v13, s[58:59]
	v_cndmask_b32_e32 v13, 0, v190, vcc
	v_sub_f32_e32 v9, v9, v13
	v_mul_f32_e32 v13, 0xbfb8aa3b, v15
	v_exp_f32_e32 v13, v13
	v_lshlrev_b32_e32 v15, 16, v3
	s_lshl_b32 s4, s11, 4
	s_lshl_b64 s[16:17], s[60:61], 20
	v_add_f32_e32 v13, 1.0, v13
	v_rcp_f32_e32 v108, v13
	v_mul_f32_e32 v13, 0xbfb8aa3b, v16
	v_exp_f32_e32 v13, v13
	v_and_b32_e32 v16, 0xffff0000, v3
	v_fma_f32 v10, v108, v110, v10
	v_cmp_gt_f32_e32 vcc, s28, v10
	v_add_f32_e32 v13, 1.0, v13
	v_rcp_f32_e32 v109, v13
	v_cndmask_b32_e64 v13, 0, 32, vcc
	v_ldexp_f32 v10, v10, v13
	v_log_f32_e32 v10, v10
	v_fmac_f32_e32 v11, v109, v111
	s_add_u32 s15, s88, s16
	s_addc_u32 s16, s89, s17
	v_mul_f32_e32 v13, 0x3f317217, v10
	v_fma_f32 v13, v10, s29, -v13
	v_fmac_f32_e32 v13, 0x3377d1cf, v10
	v_fmac_f32_e32 v13, 0x3f317217, v10
	v_cmp_lt_f32_e64 s[58:59], |v10|, s30
	s_lshl_b32 s14, s14, 15
	s_add_u32 s14, s15, s14
	v_cndmask_b32_e64 v10, v10, v13, s[58:59]
	v_cndmask_b32_e32 v13, 0, v190, vcc
	v_cmp_gt_f32_e32 vcc, s28, v11
	v_sub_f32_e32 v10, v10, v13
	s_addc_u32 s15, s16, 0
	v_cndmask_b32_e64 v13, 0, 32, vcc
	v_ldexp_f32 v11, v11, v13
	v_log_f32_e32 v11, v11
	v_mov_b32_e32 v125, v145
	v_mul_f32_e32 v13, 0x3f317217, v11
	v_fma_f32 v13, v11, s29, -v13
	v_fmac_f32_e32 v13, 0x3377d1cf, v11
	v_fmac_f32_e32 v13, 0x3f317217, v11
	v_cmp_lt_f32_e64 s[58:59], |v11|, s30
	s_nop 1
	v_cndmask_b32_e64 v11, v11, v13, s[58:59]
	v_cndmask_b32_e32 v13, 0, v190, vcc
	v_sub_f32_e32 v11, v11, v13
	v_mul_f32_e32 v13, 0xbfb8aa3b, v17
	v_exp_f32_e32 v13, v13
	s_nop 0
	v_add_f32_e32 v13, 1.0, v13
	v_rcp_f32_e32 v112, v13
	v_mul_f32_e32 v13, 0xbfb8aa3b, v18
	v_exp_f32_e32 v13, v13
	v_fma_f32 v4, v112, v114, v4
	v_cmp_gt_f32_e32 vcc, s28, v4
	v_add_f32_e32 v13, 1.0, v13
	v_rcp_f32_e32 v113, v13
	v_cndmask_b32_e64 v13, 0, 32, vcc
	v_ldexp_f32 v4, v4, v13
	v_log_f32_e32 v4, v4
	v_fma_f32 v5, v113, v115, v5
	v_mul_f32_e32 v13, 0x3f317217, v4
	v_fma_f32 v13, v4, s29, -v13
	v_fmac_f32_e32 v13, 0x3377d1cf, v4
	v_fmac_f32_e32 v13, 0x3f317217, v4
	v_cmp_lt_f32_e64 s[58:59], |v4|, s30
	s_nop 1
	v_cndmask_b32_e64 v4, v4, v13, s[58:59]
	v_cndmask_b32_e32 v13, 0, v190, vcc
	v_cmp_gt_f32_e32 vcc, s28, v5
	v_sub_f32_e32 v4, v4, v13
	s_nop 0
	v_cndmask_b32_e64 v13, 0, 32, vcc
	v_ldexp_f32 v5, v5, v13
	v_log_f32_e32 v5, v5
	s_nop 0
	v_mul_f32_e32 v13, 0x3f317217, v5
	v_fma_f32 v13, v5, s29, -v13
	v_fmac_f32_e32 v13, 0x3377d1cf, v5
	v_fmac_f32_e32 v13, 0x3f317217, v5
	v_cmp_lt_f32_e64 s[58:59], |v5|, s30
	s_nop 1
	v_cndmask_b32_e64 v5, v5, v13, s[58:59]
	v_cndmask_b32_e32 v13, 0, v190, vcc
	v_sub_f32_e32 v5, v5, v13
	v_mul_f32_e32 v13, 0xbfb8aa3b, v19
	v_exp_f32_e32 v13, v13
	s_nop 0
	v_add_f32_e32 v13, 1.0, v13
	v_rcp_f32_e32 v136, v13
	v_mul_f32_e32 v13, 0xbfb8aa3b, v20
	v_exp_f32_e32 v13, v13
	v_fma_f32 v6, v136, v138, v6
	v_cmp_gt_f32_e32 vcc, s28, v6
	v_add_f32_e32 v13, 1.0, v13
	v_rcp_f32_e32 v137, v13
	v_cndmask_b32_e64 v13, 0, 32, vcc
	v_ldexp_f32 v6, v6, v13
	v_log_f32_e32 v6, v6
	v_fmac_f32_e32 v7, v137, v139
	v_mul_f32_e32 v13, 0x3f317217, v6
	v_fma_f32 v13, v6, s29, -v13
	v_fmac_f32_e32 v13, 0x3377d1cf, v6
	v_fmac_f32_e32 v13, 0x3f317217, v6
	v_cmp_lt_f32_e64 s[58:59], |v6|, s30
	s_nop 1
	v_cndmask_b32_e64 v6, v6, v13, s[58:59]
	v_cndmask_b32_e32 v13, 0, v190, vcc
	v_cmp_gt_f32_e32 vcc, s28, v7
	v_sub_f32_e32 v6, v6, v13
	s_nop 0
	v_cndmask_b32_e64 v13, 0, 32, vcc
	v_ldexp_f32 v7, v7, v13
	v_log_f32_e32 v7, v7
	s_nop 0
	v_mul_f32_e32 v13, 0x3f317217, v7
	v_fma_f32 v13, v7, s29, -v13
	v_fmac_f32_e32 v13, 0x3377d1cf, v7
	v_fmac_f32_e32 v13, 0x3f317217, v7
	v_cmp_lt_f32_e64 s[58:59], |v7|, s30
	s_nop 1
	v_cndmask_b32_e64 v7, v7, v13, s[58:59]
	v_cndmask_b32_e32 v13, 0, v190, vcc
	v_sub_f32_e32 v7, v7, v13
	ds_write_b128 v172, v[8:11]
	ds_write_b128 v172, v[4:7] offset:16
	v_lshlrev_b32_e32 v8, 16, v0
	v_mul_f32_e32 v8, 0xbfb8aa3b, v8
	v_exp_f32_e32 v8, v8
	v_and_b32_e32 v9, 0xffff0000, v0
	v_lshlrev_b32_e32 v10, 16, v1
	v_and_b32_e32 v11, 0xffff0000, v1
	v_lshlrev_b32_e32 v13, 16, v2
	ds_read_b128 v[4:7], v12
	ds_read_b128 v[0:3], v12 offset:16
	v_add_f32_e32 v8, 1.0, v8
	v_rcp_f32_e32 v140, v8
	v_mul_f32_e32 v8, 0xbfb8aa3b, v9
	v_exp_f32_e32 v8, v8
	s_waitcnt lgkmcnt(1)
; #define LAS __attribute__((address_space(3)))
; __device__ __forceinline__ float bflo(unsigned u) { return __uint_as_float(u << 16); }
; __device__ __forceinline__ float bfhi(unsigned u) { return __uint_as_float(u & 0xffff0000u); }
; __device__ __forceinline__ float sigm(float x) { return frcp(1.f + fexp(-x)); }
; __device__ __forceinline__ void hgrn_stepA(const Args& a, int l, LAS unsigned char* lds, int tid, int hh, const HIn& in, float (&kf)[16]) {
;     ...
;     for (int ii = 0; ii < 2; ++ii) {
;         const int cid = tid + 512 * ii, t = cid >> 4, d0 = (cid & 15) * 8;
;         const u32x4 u = in.f[ii];
;         float fl[8] = {bflo(u.x), bfhi(u.x), bflo(u.y), bfhi(u.y), bflo(u.z), bfhi(u.z), bflo(u.w), bfhi(u.w)};
;         float lf[8];
;         const LAS float* LB = (const LAS float*)(lds + 106496) + hh * 128 + d0; const f32x4 lb0 = *(const LAS f32x4*)LB, lb1 = *(const LAS f32x4*)(LB + 4);
;         const float lbv[8] = {lb0.x, lb0.y, lb0.z, lb0.w, lb1.x, lb1.y, lb1.z, lb1.w};
; #pragma unroll
;         for (int i = 0; i < 8; ++i) { const float lb = lbv[i]; const float sg = sigm(fl[i]);
;             const float f = lb + (1.f - lb) * sg; lf[i] = __logf(f); kf[ii * 8 + i] = (1.f - lb) * (1.f - sg); }
;         *(LAS f32x4*)(LF + t * 128 + d0) = (f32x4){lf[0], lf[1], lf[2], lf[3]}; *(LAS f32x4*)(LF + t * 128 + d0 + 4) = (f32x4){lf[4], lf[5], lf[6], lf[7]};
;     }
; __device__ __forceinline__ void hgrn_stage3_unit(const Args& a, int l, LAS unsigned char* lds, int tid, int u, const HIn& in, HIn& nxt, int unext) {
;     ...
;     const size_t row = row0 + tt * 16 + fr;
;     const bf16_t* ST = (const bf16_t*)(a.ws + WS_H) + ((size_t)bh * 32 + c) * 16384;
;     bf16x8 stf[4][4]; u32x2 zz[4];
; #pragma unroll
;     for (int ks = 0; ks < 4; ++ks)
; #pragma unroll
;         for (int v = 0; v < 4; ++v) stf[ks][v] = *(const bf16x8*)(ST + ((vh * 4 + v) * 16 + fr) * 128 + ks * 32 + fq * 8);
	v_pk_add_f32 v[142:143], v[4:5], 1.0 op_sel_hi:[1,0] neg_lo:[1,0] neg_hi:[1,0]
	v_pk_add_f32 v[162:163], v[6:7], 1.0 op_sel_hi:[1,0] neg_lo:[1,0] neg_hi:[1,0]
	v_fma_f32 v4, v140, v142, v4
	v_add_f32_e32 v8, 1.0, v8
	v_cmp_gt_f32_e32 vcc, s28, v4
	v_rcp_f32_e32 v141, v8
	s_waitcnt lgkmcnt(0)
	v_pk_add_f32 v[166:167], v[0:1], 1.0 op_sel_hi:[1,0] neg_lo:[1,0] neg_hi:[1,0]
	v_cndmask_b32_e64 v8, 0, 32, vcc
	v_ldexp_f32 v4, v4, v8
	v_log_f32_e32 v4, v4
	v_fma_f32 v5, v141, v143, v5
	v_pk_add_f32 v[158:159], v[2:3], 1.0 op_sel_hi:[1,0] neg_lo:[1,0] neg_hi:[1,0]
	v_mul_f32_e32 v8, 0x3f317217, v4
	v_fma_f32 v8, v4, s29, -v8
	v_fmac_f32_e32 v8, 0x3377d1cf, v4
	v_fmac_f32_e32 v8, 0x3f317217, v4
	v_cmp_lt_f32_e64 s[58:59], |v4|, s30
	s_nop 1
	v_cndmask_b32_e64 v4, v4, v8, s[58:59]
	v_cndmask_b32_e32 v8, 0, v190, vcc
	v_cmp_gt_f32_e32 vcc, s28, v5
	v_sub_f32_e32 v4, v4, v8
	s_nop 0
	v_cndmask_b32_e64 v8, 0, 32, vcc
	v_ldexp_f32 v5, v5, v8
	v_log_f32_e32 v5, v5
	s_nop 0
	v_mul_f32_e32 v8, 0x3f317217, v5
	v_fma_f32 v8, v5, s29, -v8
	v_fmac_f32_e32 v8, 0x3377d1cf, v5
	v_fmac_f32_e32 v8, 0x3f317217, v5
	v_cmp_lt_f32_e64 s[58:59], |v5|, s30
	s_nop 1
	v_cndmask_b32_e64 v5, v5, v8, s[58:59]
	v_cndmask_b32_e32 v8, 0, v190, vcc
	v_sub_f32_e32 v5, v5, v8
	v_mul_f32_e32 v8, 0xbfb8aa3b, v10
	v_exp_f32_e32 v8, v8
	s_nop 0
	v_add_f32_e32 v8, 1.0, v8
	v_rcp_f32_e32 v160, v8
	v_mul_f32_e32 v8, 0xbfb8aa3b, v11
	v_exp_f32_e32 v8, v8
	v_fma_f32 v6, v160, v162, v6
	v_cmp_gt_f32_e32 vcc, s28, v6
	v_add_f32_e32 v8, 1.0, v8
	v_rcp_f32_e32 v161, v8
	v_cndmask_b32_e64 v8, 0, 32, vcc
	v_ldexp_f32 v6, v6, v8
	v_log_f32_e32 v6, v6
	v_fmac_f32_e32 v7, v161, v163
	v_mul_f32_e32 v8, 0x3f317217, v6
	v_fma_f32 v8, v6, s29, -v8
	v_fmac_f32_e32 v8, 0x3377d1cf, v6
	v_fmac_f32_e32 v8, 0x3f317217, v6
	v_cmp_lt_f32_e64 s[58:59], |v6|, s30
	s_nop 1
	v_cndmask_b32_e64 v6, v6, v8, s[58:59]
	v_cndmask_b32_e32 v8, 0, v190, vcc
	v_cmp_gt_f32_e32 vcc, s28, v7
	v_sub_f32_e32 v6, v6, v8
	s_nop 0
	v_cndmask_b32_e64 v8, 0, 32, vcc
	v_ldexp_f32 v7, v7, v8
	v_log_f32_e32 v7, v7
	s_nop 0
	v_mul_f32_e32 v8, 0x3f317217, v7
	v_fma_f32 v8, v7, s29, -v8
	v_fmac_f32_e32 v8, 0x3377d1cf, v7
	v_fmac_f32_e32 v8, 0x3f317217, v7
	v_cmp_lt_f32_e64 s[58:59], |v7|, s30
	s_nop 1
	v_cndmask_b32_e64 v7, v7, v8, s[58:59]
	v_cndmask_b32_e32 v8, 0, v190, vcc
	v_sub_f32_e32 v7, v7, v8
	v_mul_f32_e32 v8, 0xbfb8aa3b, v13
	v_exp_f32_e32 v8, v8
	s_nop 0
	v_add_f32_e32 v8, 1.0, v8
	v_rcp_f32_e32 v164, v8
	v_mul_f32_e32 v8, 0xbfb8aa3b, v14
	v_exp_f32_e32 v8, v8
	v_fma_f32 v0, v164, v166, v0
	v_cmp_gt_f32_e32 vcc, s28, v0
	v_add_f32_e32 v8, 1.0, v8
	v_rcp_f32_e32 v165, v8
	v_cndmask_b32_e64 v8, 0, 32, vcc
	v_ldexp_f32 v0, v0, v8
	v_log_f32_e32 v0, v0
	v_fma_f32 v1, v165, v167, v1
	v_mul_f32_e32 v8, 0x3f317217, v0
	v_fma_f32 v8, v0, s29, -v8
	v_fmac_f32_e32 v8, 0x3377d1cf, v0
	v_fmac_f32_e32 v8, 0x3f317217, v0
	v_cmp_lt_f32_e64 s[58:59], |v0|, s30
	s_nop 1
	v_cndmask_b32_e64 v0, v0, v8, s[58:59]
	v_cndmask_b32_e32 v8, 0, v190, vcc
	v_cmp_gt_f32_e32 vcc, s28, v1
	v_sub_f32_e32 v0, v0, v8
	s_nop 0
	v_cndmask_b32_e64 v8, 0, 32, vcc
	v_ldexp_f32 v1, v1, v8
	v_log_f32_e32 v1, v1
	s_nop 0
	v_mul_f32_e32 v8, 0x3f317217, v1
	v_fma_f32 v8, v1, s29, -v8
	v_fmac_f32_e32 v8, 0x3377d1cf, v1
	v_fmac_f32_e32 v8, 0x3f317217, v1
	v_cmp_lt_f32_e64 s[58:59], |v1|, s30
	s_nop 1
	v_cndmask_b32_e64 v1, v1, v8, s[58:59]
	v_cndmask_b32_e32 v8, 0, v190, vcc
	v_sub_f32_e32 v1, v1, v8
	v_mul_f32_e32 v8, 0xbfb8aa3b, v15
	v_exp_f32_e32 v8, v8
	s_nop 0
	v_add_f32_e32 v8, 1.0, v8
	v_rcp_f32_e32 v156, v8
	v_mul_f32_e32 v8, 0xbfb8aa3b, v16
	v_exp_f32_e32 v8, v8
	v_fma_f32 v2, v156, v158, v2
	v_cmp_gt_f32_e32 vcc, s28, v2
	v_add_f32_e32 v8, 1.0, v8
	v_rcp_f32_e32 v157, v8
	v_cndmask_b32_e64 v8, 0, 32, vcc
	v_ldexp_f32 v2, v2, v8
	v_log_f32_e32 v2, v2
	v_fmac_f32_e32 v3, v157, v159
	v_mul_f32_e32 v8, 0x3f317217, v2
	v_fma_f32 v8, v2, s29, -v8
	v_fmac_f32_e32 v8, 0x3377d1cf, v2
	v_fmac_f32_e32 v8, 0x3f317217, v2
	v_cmp_lt_f32_e64 s[58:59], |v2|, s30
	s_nop 1
	v_cndmask_b32_e64 v2, v2, v8, s[58:59]
	v_cndmask_b32_e32 v8, 0, v190, vcc
	v_cmp_gt_f32_e32 vcc, s28, v3
	v_sub_f32_e32 v2, v2, v8
	s_nop 0
	v_cndmask_b32_e64 v8, 0, 32, vcc
	v_ldexp_f32 v3, v3, v8
	v_log_f32_e32 v3, v3
	s_nop 0
	v_mul_f32_e32 v8, 0x3f317217, v3
	v_fma_f32 v8, v3, s29, -v8
	v_fmac_f32_e32 v8, 0x3377d1cf, v3
	v_fmac_f32_e32 v8, 0x3f317217, v3
	v_cmp_lt_f32_e64 s[58:59], |v3|, s30
	s_nop 1
	v_cndmask_b32_e64 v3, v3, v8, s[58:59]
	v_cndmask_b32_e32 v8, 0, v190, vcc
	v_sub_f32_e32 v3, v3, v8
	ds_write_b128 v172, v[4:7] offset:16384
	ds_write_b128 v172, v[0:3] offset:16400
	v_lshlrev_b32_e32 v14, 3, v120
	s_mov_b64 s[16:17], 0x400
	s_mov_b64 s[18:19], 0x800
	v_lshl_or_b32 v2, s36, 13, v14
	v_or_b32_e32 v6, 0x800, v2
	v_ashrrev_i32_e32 v7, 31, v6
	v_lshl_add_u64 v[0:1], v[144:145], 4, s[14:15]
	v_lshlrev_b64 v[6:7], 1, v[6:7]
	v_lshl_add_u64 v[8:9], v[0:1], 0, v[6:7]
	v_ashrrev_i32_e32 v3, 31, v2
	global_load_dwordx4 v[60:63], v[8:9], off
; #define LAS __attribute__((address_space(3)))
; #define BAR_LDS() do { asm volatile("s_waitcnt lgkmcnt(0)" ::: "memory"); __builtin_amdgcn_s_barrier(); asm volatile("" ::: "memory"); } while (0)
; __device__ __forceinline__ void hgrn_cumsum_scan(LAS unsigned char* lds, int tid) {
;     LAS float* LF = (LAS float*)lds;
;     LAS float* PT = (LAS float*)(lds + 32768);
;     BAR_LDS();
;     const int d = tid & 127, pt = tid >> 7;
;     float v[16];
; #pragma unroll
;     for (int t = 0; t < 16; ++t) v[t] = LF[(pt * 16 + t) * 128 + d];
; #pragma unroll
;     for (int t = 1; t < 16; ++t) v[t] += v[t - 1];
;     PT[pt * 128 + d] = v[15];
;     BAR_LDS();
; __device__ __forceinline__ void hgrn_stage3_unit(const Args& a, int l, LAS unsigned char* lds, int tid, int u, const HIn& in, HIn& nxt, int unext) {
;     ...
;     const size_t row = row0 + tt * 16 + fr;
;     const bf16_t* ST = (const bf16_t*)(a.ws + WS_H) + ((size_t)bh * 32 + c) * 16384;
;     bf16x8 stf[4][4]; u32x2 zz[4];
; #pragma unroll
;     for (int ks = 0; ks < 4; ++ks)
; #pragma unroll
;         for (int v = 0; v < 4; ++v) stf[ks][v] = *(const bf16x8*)(ST + ((vh * 4 + v) * 16 + fr) * 128 + ks * 32 + fq * 8);
; #pragma unroll
;     for (int v = 0; v < 4; ++v) zz[v] = *(const u32x2*)(proj + row * NCOL + CZ + 512 + hh * 128 + (vh * 4 + v) * 16 + fq * 4);
;     hgrn_load<true>(a, tid, unext, nxt);
;     hgrn_cumsum_scan(lds, tid);
	v_or_b32_e32 v8, 0x1000, v2
	v_lshl_add_u64 v[4:5], v[2:3], 1, v[0:1]
	v_ashrrev_i32_e32 v9, 31, v8
	v_or_b32_e32 v2, 0x1800, v2
	v_lshlrev_b64 v[8:9], 1, v[8:9]
	v_ashrrev_i32_e32 v3, 31, v2
	v_lshl_add_u64 v[10:11], v[0:1], 0, v[8:9]
	v_lshlrev_b64 v[2:3], 1, v[2:3]
	global_load_dwordx4 v[92:95], v[10:11], off
	v_lshl_add_u64 v[10:11], v[0:1], 0, v[2:3]
	global_load_dwordx4 v[96:99], v[10:11], off
	v_lshl_add_u64 v[10:11], v[0:1], 0, s[16:17]
	v_lshl_add_u64 v[12:13], v[10:11], 0, v[6:7]
	global_load_dwordx4 v[40:43], v[12:13], off
	v_lshl_add_u64 v[12:13], v[10:11], 0, v[8:9]
	v_lshl_add_u64 v[10:11], v[10:11], 0, v[2:3]
	global_load_dwordx4 v[44:47], v[12:13], off
	global_load_dwordx4 v[52:55], v[10:11], off
	v_lshl_add_u64 v[10:11], v[0:1], 0, s[18:19]
	s_mov_b64 s[14:15], 0xc00
	v_lshl_add_u64 v[12:13], v[10:11], 0, v[6:7]
	v_lshl_add_u64 v[0:1], v[0:1], 0, s[14:15]
	s_lshl_b64 s[14:15], s[40:41], 11
	global_load_dwordx4 v[36:39], v[4:5], off
	global_load_dwordx4 v[32:35], v[4:5], off offset:1024
	global_load_dwordx4 v[56:59], v[4:5], off offset:2048
	global_load_dwordx4 v[48:51], v[4:5], off offset:3072
	global_load_dwordx4 v[76:79], v[12:13], off
	v_lshl_add_u64 v[12:13], v[10:11], 0, v[8:9]
	v_lshl_add_u64 v[10:11], v[10:11], 0, v[2:3]
	v_lshl_add_u64 v[4:5], v[0:1], 0, v[6:7]
	s_or_b32 s6, s14, s6
	global_load_dwordx4 v[88:91], v[10:11], off
	global_load_dwordx4 v[64:67], v[4:5], off
	v_lshl_add_u64 v[4:5], v[0:1], 0, v[8:9]
	v_lshl_add_u64 v[0:1], v[0:1], 0, v[2:3]
	s_or_b32 s6, s6, s4
	global_load_dwordx4 v[68:71], v[4:5], off
	global_load_dwordx4 v[80:83], v[0:1], off
	v_mov_b32_e32 v1, s15
	v_or_b32_e32 v0, s6, v120
	v_lshlrev_b64 v[0:1], 13, v[0:1]
	v_lshl_add_u64 v[134:135], s[84:85], 0, v[0:1]
	s_lshl_b32 s6, s9, 8
	v_lshl_add_u64 v[0:1], v[134:135], 0, s[6:7]
	s_lshl_b32 s40, s36, 6
	v_lshlrev_b32_e32 v2, 1, v122
	v_mov_b32_e32 v3, v145
	v_lshl_add_u64 v[0:1], v[0:1], 0, v[2:3]
	s_ashr_i32 s41, s40, 31
	s_ashr_i32 s14, s5, 7
	v_lshl_add_u64 v[0:1], s[40:41], 1, v[0:1]
	s_ashr_i32 s15, s14, 31
	s_lshl_b32 s6, s5, 6
	v_lshl_add_u64 v[2:3], v[0:1], 0, s[12:13]
	v_add_co_u32_e32 v0, vcc, s26, v0
	s_lshl_b64 s[14:15], s[14:15], 11
	s_and_b32 s6, s6, 0x7c0
	v_addc_co_u32_e32 v1, vcc, 0, v1, vcc
	s_or_b32 s14, s14, s6
	global_load_dwordx4 v[84:87], v[12:13], off
	global_load_dwordx2 v[132:133], v[0:1], off
	global_load_dwordx2 v[130:131], v[2:3], off offset:32
	global_load_dwordx2 v[128:129], v[2:3], off offset:64
	global_load_dwordx2 v[126:127], v[2:3], off offset:96
	v_lshl_add_u64 v[0:1], s[14:15], 0, v[116:117]
	v_lshlrev_b64 v[0:1], 13, v[0:1]
	s_lshl_b32 s5, s5, 3
	v_lshl_add_u64 v[0:1], s[84:85], 0, v[0:1]
	s_and_b32 s6, s5, 0x300
	v_lshl_add_u64 v[0:1], v[0:1], 0, s[6:7]
	v_lshl_add_u64 v[0:1], v[0:1], 0, v[124:125]
	v_add_co_u32_e32 v2, vcc, s26, v0
	s_nop 1
	v_addc_co_u32_e32 v3, vcc, 0, v1, vcc
	global_load_dwordx4 v[4:7], v[2:3], off offset:2048
	global_load_dwordx4 v[8:11], v[2:3], off offset:3072
	global_load_dwordx4 v[12:15], v[0:1], off offset:1024
	v_lshl_add_u64 v[0:1], s[14:15], 0, v[118:119]
	v_lshlrev_b64 v[0:1], 13, v[0:1]
	v_lshl_add_u64 v[0:1], s[84:85], 0, v[0:1]
	v_lshl_add_u64 v[0:1], v[0:1], 0, s[6:7]
	v_lshl_add_u64 v[20:21], v[0:1], 0, v[124:125]
	v_add_co_u32_e32 v16, vcc, s26, v20
	s_nop 1
	v_addc_co_u32_e32 v17, vcc, 0, v21, vcc
	global_load_dwordx4 v[0:3], v[16:17], off offset:2048
	s_nop 0
	global_load_dwordx4 v[16:19], v[16:17], off offset:3072
	s_nop 0
	global_load_dwordx4 v[20:23], v[20:21], off offset:1024
	s_waitcnt lgkmcnt(0)
	s_barrier
	ds_read2st64_b32 v[168:169], v175 offset1:2
	ds_read2st64_b32 v[206:207], v175 offset0:4 offset1:6
	ds_read2st64_b32 v[208:209], v175 offset0:8 offset1:10
	ds_read2st64_b32 v[218:219], v175 offset0:12 offset1:14
	ds_read2st64_b32 v[220:221], v175 offset0:16 offset1:18
	ds_read2st64_b32 v[222:223], v175 offset0:20 offset1:22
	ds_read2st64_b32 v[224:225], v175 offset0:24 offset1:26
	ds_read2st64_b32 v[226:227], v175 offset0:28 offset1:30
	s_waitcnt lgkmcnt(7)
	v_add_f32_e32 v217, v168, v169
	s_waitcnt lgkmcnt(6)
	v_add_f32_e32 v215, v206, v217
	v_add_f32_e32 v216, v207, v215
	s_waitcnt lgkmcnt(5)
	v_add_f32_e32 v213, v208, v216
	v_add_f32_e32 v214, v209, v213
	s_waitcnt lgkmcnt(4)
	v_add_f32_e32 v211, v218, v214
	v_add_f32_e32 v212, v219, v211
	s_waitcnt lgkmcnt(3)
	v_add_f32_e32 v209, v220, v212
	v_add_f32_e32 v210, v221, v209
	s_waitcnt lgkmcnt(2)
	v_add_f32_e32 v207, v222, v210
	v_add_f32_e32 v208, v223, v207
	s_waitcnt lgkmcnt(1)
	v_add_f32_e32 v205, v224, v208
	v_add_f32_e32 v206, v225, v205
	s_waitcnt lgkmcnt(0)
	v_add_f32_e32 v125, v226, v206
	v_add_f32_e32 v169, v227, v125
	ds_write_b32 v123, v169 offset:32768
	s_waitcnt lgkmcnt(0)
	s_barrier
	v_mov_b32_e32 v218, 0
	v_mov_b32_e32 v219, 0
	s_and_saveexec_b64 s[14:15], s[42:43]
	s_cbranch_execnz .LBB0_654
	s_or_b64 exec, exec, s[14:15]
	v_mov_b32_e32 v220, 0
	s_and_saveexec_b64 s[14:15], s[44:45]
	s_cbranch_execnz .LBB0_655

; __device__ __forceinline__ unsigned pk2(float lo, float hi) { f32x2_t v = {lo, hi}; bf16x2_t b = __builtin_convertvector(v, bf16x2_t); return __builtin_bit_cast(unsigned, b); }
; __device__ __forceinline__ float bflo(unsigned u) { return __uint_as_float(u << 16); }
; __device__ __forceinline__ float bfhi(unsigned u) { return __uint_as_float(u & 0xffff0000u); }
; __device__ __forceinline__ int otid() { int t = threadIdx.x; asm volatile("" : "+v"(t)); return t; }
; __device__ __forceinline__ void hgrn_scan_phase(const Args& a) {
;     const int id = blockIdx.x * 512 + otid(), NT = gridDim.x * 512;
;     for (int it = id; it < 32 * 128 * 32; it += NT) {
;         const int bh = it >> 12, dv = (it >> 5) & 127, dkc = it & 31;
;         u32x2* st = (u32x2*)((bf16_t*)(a.ws + WS_H) + (size_t)bh * 32 * 16384 + dv * 128 + dkc * 4);
;         const f32x4* dc = (const f32x4*)((const float*)(a.ws + WS_DECAY) + (size_t)bh * 32 * 128 + dkc * 4);
;         float r0 = 0.f, r1 = 0.f, r2 = 0.f, r3 = 0.f;
; #pragma unroll 8
;         for (int c = 0; c < 32; ++c) {
;             const u32x2 u = st[(size_t)c * 4096]; const f32x4 dd = dc[c * 32];
;             u32x2 o; o.x = pk2(r0, r1); o.y = pk2(r2, r3); st[(size_t)c * 4096] = o;
;             r0 = dd.x * r0 + bflo(u.x); r1 = dd.y * r1 + bfhi(u.x); r2 = dd.z * r2 + bflo(u.y); r3 = dd.w * r3 + bfhi(u.y);
;         }
.Lscan_fast:
	v_lshrrev_b32_e32 v222, 12, v12
	v_and_b32_e32 v220, 0xfff, v12
	v_bfe_u32 v221, v12, 5, 4
	v_and_b32_e32 v216, 1, v12
	v_lshl_or_b32 v221, v221, 1, v216
	v_lshlrev_b32_e32 v220, 3, v220
	v_lshlrev_b32_e32 v221, 4, v221
	v_lshl_or_b32 v220, v222, 20, v220
	v_lshl_or_b32 v221, v222, 14, v221
	s_add_u32 s10, s78, 0x1e00000
	s_addc_u32 s11, s79, 0
	s_mov_b32 s14, s10
	s_mov_b32 s15, s11
	s_add_u32 s8, s78, 0xf620000
	s_addc_u32 s9, s79, 0
	v_mov_b32_e32 v208, 0
	v_mov_b32_e32 v209, 0
	v_mov_b32_e32 v210, 0
	v_mov_b32_e32 v211, 0
	global_load_dwordx2 v[128:129], v220, s[10:11]
	s_add_u32 s10, s10, 0x8000
	s_addc_u32 s11, s11, 0
	global_load_dwordx4 v[12:15], v221, s[8:9]
	global_load_dwordx2 v[130:131], v220, s[10:11]
	s_add_u32 s10, s10, 0x8000
	s_addc_u32 s11, s11, 0
	global_load_dwordx4 v[16:19], v221, s[8:9] offset:512
	global_load_dwordx2 v[132:133], v220, s[10:11]
	s_add_u32 s10, s10, 0x8000
	s_addc_u32 s11, s11, 0
	global_load_dwordx4 v[20:23], v221, s[8:9] offset:1024
	global_load_dwordx2 v[134:135], v220, s[10:11]
	s_add_u32 s10, s10, 0x8000
	s_addc_u32 s11, s11, 0
	global_load_dwordx4 v[24:27], v221, s[8:9] offset:1536
	global_load_dwordx2 v[136:137], v220, s[10:11]
	s_add_u32 s10, s10, 0x8000
	s_addc_u32 s11, s11, 0
	global_load_dwordx4 v[28:31], v221, s[8:9] offset:2048
	global_load_dwordx2 v[138:139], v220, s[10:11]
	s_add_u32 s10, s10, 0x8000
	s_addc_u32 s11, s11, 0
	global_load_dwordx4 v[32:35], v221, s[8:9] offset:2560
	global_load_dwordx2 v[140:141], v220, s[10:11]
	s_add_u32 s10, s10, 0x8000
	s_addc_u32 s11, s11, 0
	global_load_dwordx4 v[36:39], v221, s[8:9] offset:3072
	global_load_dwordx2 v[142:143], v220, s[10:11]
	s_add_u32 s10, s10, 0x8000
	s_addc_u32 s11, s11, 0
	global_load_dwordx4 v[40:43], v221, s[8:9] offset:3584
	s_add_u32 s8, s8, 0x1000
	s_addc_u32 s9, s9, 0
	global_load_dwordx2 v[156:157], v220, s[10:11]
	s_add_u32 s10, s10, 0x8000
	s_addc_u32 s11, s11, 0
	global_load_dwordx4 v[44:47], v221, s[8:9]
	global_load_dwordx2 v[158:159], v220, s[10:11]
	s_add_u32 s10, s10, 0x8000
	s_addc_u32 s11, s11, 0
	global_load_dwordx4 v[48:51], v221, s[8:9] offset:512
	global_load_dwordx2 v[160:161], v220, s[10:11]
	s_add_u32 s10, s10, 0x8000
	s_addc_u32 s11, s11, 0
	global_load_dwordx4 v[52:55], v221, s[8:9] offset:1024
	global_load_dwordx2 v[162:163], v220, s[10:11]
	s_add_u32 s10, s10, 0x8000
	s_addc_u32 s11, s11, 0
	global_load_dwordx4 v[56:59], v221, s[8:9] offset:1536
	global_load_dwordx2 v[164:165], v220, s[10:11]
	s_add_u32 s10, s10, 0x8000
	s_addc_u32 s11, s11, 0
	global_load_dwordx4 v[60:63], v221, s[8:9] offset:2048
	global_load_dwordx2 v[166:167], v220, s[10:11]
	s_add_u32 s10, s10, 0x8000
	s_addc_u32 s11, s11, 0
	global_load_dwordx4 v[64:67], v221, s[8:9] offset:2560
	global_load_dwordx2 v[168:169], v220, s[10:11]
	s_add_u32 s10, s10, 0x8000
	s_addc_u32 s11, s11, 0
	global_load_dwordx4 v[68:71], v221, s[8:9] offset:3072
	global_load_dwordx2 v[170:171], v220, s[10:11]
	s_add_u32 s10, s10, 0x8000
	s_addc_u32 s11, s11, 0
	global_load_dwordx4 v[72:75], v221, s[8:9] offset:3584
	s_add_u32 s8, s8, 0x1000
	s_addc_u32 s9, s9, 0
	global_load_dwordx2 v[172:173], v220, s[10:11]
	s_add_u32 s10, s10, 0x8000
	s_addc_u32 s11, s11, 0
	global_load_dwordx4 v[76:79], v221, s[8:9]
	global_load_dwordx2 v[174:175], v220, s[10:11]
	s_add_u32 s10, s10, 0x8000
	s_addc_u32 s11, s11, 0
	global_load_dwordx4 v[84:87], v221, s[8:9] offset:512
	global_load_dwordx2 v[196:197], v220, s[10:11]
	s_add_u32 s10, s10, 0x8000
	s_addc_u32 s11, s11, 0
	global_load_dwordx4 v[88:91], v221, s[8:9] offset:1024
	global_load_dwordx2 v[198:199], v220, s[10:11]
	s_add_u32 s10, s10, 0x8000
	s_addc_u32 s11, s11, 0
	global_load_dwordx4 v[92:95], v221, s[8:9] offset:1536
	global_load_dwordx2 v[200:201], v220, s[10:11]
	s_add_u32 s10, s10, 0x8000
	s_addc_u32 s11, s11, 0
	global_load_dwordx4 v[100:103], v221, s[8:9] offset:2048
	global_load_dwordx2 v[202:203], v220, s[10:11]
	s_add_u32 s10, s10, 0x8000
	s_addc_u32 s11, s11, 0
	global_load_dwordx4 v[104:107], v221, s[8:9] offset:2560
	global_load_dwordx2 v[204:205], v220, s[10:11]
	s_add_u32 s10, s10, 0x8000
	s_addc_u32 s11, s11, 0
	global_load_dwordx4 v[108:111], v221, s[8:9] offset:3072
	global_load_dwordx2 v[206:207], v220, s[10:11]
	s_add_u32 s10, s10, 0x8000
	s_addc_u32 s11, s11, 0
	global_load_dwordx4 v[112:115], v221, s[8:9] offset:3584
	s_add_u32 s8, s8, 0x1000
	s_addc_u32 s9, s9, 0
	v_cvt_pk_bf16_f32 v216, v208, v209
	v_cvt_pk_bf16_f32 v217, v210, v211
	global_store_dwordx2 v220, v[216:217], s[14:15]
	s_add_u32 s14, s14, 0x8000
	s_addc_u32 s15, s15, 0
	s_waitcnt vmcnt(48)
	v_lshlrev_b32_e32 v212, 16, v128
	v_and_b32_e32 v213, 0xffff0000, v128
	v_lshlrev_b32_e32 v214, 16, v129
	v_and_b32_e32 v215, 0xffff0000, v129
	s_waitcnt vmcnt(47)
	v_pk_fma_f32 v[208:209], v[208:209], v[12:13], v[212:213]
	v_pk_fma_f32 v[210:211], v[210:211], v[14:15], v[214:215]
	global_load_dwordx2 v[128:129], v220, s[10:11]
	s_add_u32 s10, s10, 0x8000
	s_addc_u32 s11, s11, 0
	global_load_dwordx4 v[12:15], v221, s[8:9]
	v_cvt_pk_bf16_f32 v218, v208, v209
	v_cvt_pk_bf16_f32 v219, v210, v211
	global_store_dwordx2 v220, v[218:219], s[14:15]
	s_add_u32 s14, s14, 0x8000
	s_addc_u32 s15, s15, 0
	s_waitcnt vmcnt(49)
	v_lshlrev_b32_e32 v212, 16, v130
	v_and_b32_e32 v213, 0xffff0000, v130
	v_lshlrev_b32_e32 v214, 16, v131
	v_and_b32_e32 v215, 0xffff0000, v131
	s_waitcnt vmcnt(48)
	v_pk_fma_f32 v[208:209], v[208:209], v[16:17], v[212:213]
	v_pk_fma_f32 v[210:211], v[210:211], v[18:19], v[214:215]
	global_load_dwordx2 v[130:131], v220, s[10:11]
	s_add_u32 s10, s10, 0x8000
	s_addc_u32 s11, s11, 0
	global_load_dwordx4 v[16:19], v221, s[8:9] offset:512
	v_cvt_pk_bf16_f32 v216, v208, v209
	v_cvt_pk_bf16_f32 v217, v210, v211
	global_store_dwordx2 v220, v[216:217], s[14:15]
	s_add_u32 s14, s14, 0x8000
	s_addc_u32 s15, s15, 0
	s_waitcnt vmcnt(50)
; __device__ __forceinline__ unsigned pk2(float lo, float hi) { f32x2_t v = {lo, hi}; bf16x2_t b = __builtin_convertvector(v, bf16x2_t); return __builtin_bit_cast(unsigned, b); }
; __device__ __forceinline__ float bflo(unsigned u) { return __uint_as_float(u << 16); }
; __device__ __forceinline__ float bfhi(unsigned u) { return __uint_as_float(u & 0xffff0000u); }
; __device__ __forceinline__ void hgrn_scan_phase(const Args& a) {
;     ...
;         const f32x4* dc = (const f32x4*)((const float*)(a.ws + WS_DECAY) + (size_t)bh * 32 * 128 + dkc * 4);
;         float r0 = 0.f, r1 = 0.f, r2 = 0.f, r3 = 0.f;
; #pragma unroll 8
;         for (int c = 0; c < 32; ++c) {
;             const u32x2 u = st[(size_t)c * 4096]; const f32x4 dd = dc[c * 32];
;             u32x2 o; o.x = pk2(r0, r1); o.y = pk2(r2, r3); st[(size_t)c * 4096] = o;
;             r0 = dd.x * r0 + bflo(u.x); r1 = dd.y * r1 + bfhi(u.x); r2 = dd.z * r2 + bflo(u.y); r3 = dd.w * r3 + bfhi(u.y);
;         }
	v_lshlrev_b32_e32 v212, 16, v132
	v_and_b32_e32 v213, 0xffff0000, v132
	v_lshlrev_b32_e32 v214, 16, v133
	v_and_b32_e32 v215, 0xffff0000, v133
	s_waitcnt vmcnt(49)
	v_pk_fma_f32 v[208:209], v[208:209], v[20:21], v[212:213]
	v_pk_fma_f32 v[210:211], v[210:211], v[22:23], v[214:215]
	global_load_dwordx2 v[132:133], v220, s[10:11]
	s_add_u32 s10, s10, 0x8000
	s_addc_u32 s11, s11, 0
	global_load_dwordx4 v[20:23], v221, s[8:9] offset:1024
	v_cvt_pk_bf16_f32 v218, v208, v209
	v_cvt_pk_bf16_f32 v219, v210, v211
	global_store_dwordx2 v220, v[218:219], s[14:15]
	s_add_u32 s14, s14, 0x8000
	s_addc_u32 s15, s15, 0
	s_waitcnt vmcnt(51)
	v_lshlrev_b32_e32 v212, 16, v134
	v_and_b32_e32 v213, 0xffff0000, v134
	v_lshlrev_b32_e32 v214, 16, v135
	v_and_b32_e32 v215, 0xffff0000, v135
	s_waitcnt vmcnt(50)
	v_pk_fma_f32 v[208:209], v[208:209], v[24:25], v[212:213]
	v_pk_fma_f32 v[210:211], v[210:211], v[26:27], v[214:215]
	global_load_dwordx2 v[134:135], v220, s[10:11]
	s_add_u32 s10, s10, 0x8000
	s_addc_u32 s11, s11, 0
	global_load_dwordx4 v[24:27], v221, s[8:9] offset:1536
	v_cvt_pk_bf16_f32 v216, v208, v209
	v_cvt_pk_bf16_f32 v217, v210, v211
	global_store_dwordx2 v220, v[216:217], s[14:15]
	s_add_u32 s14, s14, 0x8000
	s_addc_u32 s15, s15, 0
	s_waitcnt vmcnt(52)
	v_lshlrev_b32_e32 v212, 16, v136
	v_and_b32_e32 v213, 0xffff0000, v136
	v_lshlrev_b32_e32 v214, 16, v137
	v_and_b32_e32 v215, 0xffff0000, v137
	s_waitcnt vmcnt(51)
	v_pk_fma_f32 v[208:209], v[208:209], v[28:29], v[212:213]
	v_pk_fma_f32 v[210:211], v[210:211], v[30:31], v[214:215]
	global_load_dwordx2 v[136:137], v220, s[10:11]
	s_add_u32 s10, s10, 0x8000
	s_addc_u32 s11, s11, 0
	global_load_dwordx4 v[28:31], v221, s[8:9] offset:2048
	v_cvt_pk_bf16_f32 v218, v208, v209
	v_cvt_pk_bf16_f32 v219, v210, v211
	global_store_dwordx2 v220, v[218:219], s[14:15]
	s_add_u32 s14, s14, 0x8000
	s_addc_u32 s15, s15, 0
	s_waitcnt vmcnt(53)
	v_lshlrev_b32_e32 v212, 16, v138
	v_and_b32_e32 v213, 0xffff0000, v138
	v_lshlrev_b32_e32 v214, 16, v139
	v_and_b32_e32 v215, 0xffff0000, v139
	s_waitcnt vmcnt(52)
	v_pk_fma_f32 v[208:209], v[208:209], v[32:33], v[212:213]
	v_pk_fma_f32 v[210:211], v[210:211], v[34:35], v[214:215]
	global_load_dwordx2 v[138:139], v220, s[10:11]
	s_add_u32 s10, s10, 0x8000
	s_addc_u32 s11, s11, 0
	global_load_dwordx4 v[32:35], v221, s[8:9] offset:2560
	v_cvt_pk_bf16_f32 v216, v208, v209
	v_cvt_pk_bf16_f32 v217, v210, v211
	global_store_dwordx2 v220, v[216:217], s[14:15]
	s_add_u32 s14, s14, 0x8000
	s_addc_u32 s15, s15, 0
	s_waitcnt vmcnt(54)
	v_lshlrev_b32_e32 v212, 16, v140
	v_and_b32_e32 v213, 0xffff0000, v140
	v_lshlrev_b32_e32 v214, 16, v141
	v_and_b32_e32 v215, 0xffff0000, v141
	s_waitcnt vmcnt(53)
	v_pk_fma_f32 v[208:209], v[208:209], v[36:37], v[212:213]
	v_pk_fma_f32 v[210:211], v[210:211], v[38:39], v[214:215]
	global_load_dwordx2 v[140:141], v220, s[10:11]
	s_add_u32 s10, s10, 0x8000
	s_addc_u32 s11, s11, 0
	global_load_dwordx4 v[36:39], v221, s[8:9] offset:3072
	v_cvt_pk_bf16_f32 v218, v208, v209
	v_cvt_pk_bf16_f32 v219, v210, v211
	global_store_dwordx2 v220, v[218:219], s[14:15]
	s_add_u32 s14, s14, 0x8000
	s_addc_u32 s15, s15, 0
	s_waitcnt vmcnt(55)
	v_lshlrev_b32_e32 v212, 16, v142
	v_and_b32_e32 v213, 0xffff0000, v142
	v_lshlrev_b32_e32 v214, 16, v143
	v_and_b32_e32 v215, 0xffff0000, v143
	s_waitcnt vmcnt(54)
	v_pk_fma_f32 v[208:209], v[208:209], v[40:41], v[212:213]
	v_pk_fma_f32 v[210:211], v[210:211], v[42:43], v[214:215]
	global_load_dwordx2 v[142:143], v220, s[10:11]
	s_add_u32 s10, s10, 0x8000
	s_addc_u32 s11, s11, 0
	global_load_dwordx4 v[40:43], v221, s[8:9] offset:3584
	s_add_u32 s8, s8, 0x1000
	s_addc_u32 s9, s9, 0
	v_cvt_pk_bf16_f32 v216, v208, v209
	v_cvt_pk_bf16_f32 v217, v210, v211
	global_store_dwordx2 v220, v[216:217], s[14:15]
	s_add_u32 s14, s14, 0x8000
	s_addc_u32 s15, s15, 0
	s_waitcnt vmcnt(56)
	v_lshlrev_b32_e32 v212, 16, v156
	v_and_b32_e32 v213, 0xffff0000, v156
	v_lshlrev_b32_e32 v214, 16, v157
	v_and_b32_e32 v215, 0xffff0000, v157
	s_waitcnt vmcnt(55)
	v_pk_fma_f32 v[208:209], v[208:209], v[44:45], v[212:213]
	v_pk_fma_f32 v[210:211], v[210:211], v[46:47], v[214:215]
	v_cvt_pk_bf16_f32 v218, v208, v209
	v_cvt_pk_bf16_f32 v219, v210, v211
	global_store_dwordx2 v220, v[218:219], s[14:15]
	s_add_u32 s14, s14, 0x8000
	s_addc_u32 s15, s15, 0
	s_waitcnt vmcnt(55)
	v_lshlrev_b32_e32 v212, 16, v158
	v_and_b32_e32 v213, 0xffff0000, v158
	v_lshlrev_b32_e32 v214, 16, v159
	v_and_b32_e32 v215, 0xffff0000, v159
	s_waitcnt vmcnt(54)
	v_pk_fma_f32 v[208:209], v[208:209], v[48:49], v[212:213]
	v_pk_fma_f32 v[210:211], v[210:211], v[50:51], v[214:215]
	v_cvt_pk_bf16_f32 v216, v208, v209
	v_cvt_pk_bf16_f32 v217, v210, v211
	global_store_dwordx2 v220, v[216:217], s[14:15]
	s_add_u32 s14, s14, 0x8000
	s_addc_u32 s15, s15, 0
	s_waitcnt vmcnt(54)
	v_lshlrev_b32_e32 v212, 16, v160
	v_and_b32_e32 v213, 0xffff0000, v160
	v_lshlrev_b32_e32 v214, 16, v161
	v_and_b32_e32 v215, 0xffff0000, v161
	s_waitcnt vmcnt(53)
	v_pk_fma_f32 v[208:209], v[208:209], v[52:53], v[212:213]
	v_pk_fma_f32 v[210:211], v[210:211], v[54:55], v[214:215]
	v_cvt_pk_bf16_f32 v218, v208, v209
	v_cvt_pk_bf16_f32 v219, v210, v211
	global_store_dwordx2 v220, v[218:219], s[14:15]
	s_add_u32 s14, s14, 0x8000
	s_addc_u32 s15, s15, 0
	s_waitcnt vmcnt(53)
	v_lshlrev_b32_e32 v212, 16, v162
	v_and_b32_e32 v213, 0xffff0000, v162
	v_lshlrev_b32_e32 v214, 16, v163
	v_and_b32_e32 v215, 0xffff0000, v163
	s_waitcnt vmcnt(52)
	v_pk_fma_f32 v[208:209], v[208:209], v[56:57], v[212:213]
	v_pk_fma_f32 v[210:211], v[210:211], v[58:59], v[214:215]
	v_cvt_pk_bf16_f32 v216, v208, v209
	v_cvt_pk_bf16_f32 v217, v210, v211
	global_store_dwordx2 v220, v[216:217], s[14:15]
	s_add_u32 s14, s14, 0x8000
	s_addc_u32 s15, s15, 0
	s_waitcnt vmcnt(52)
; __device__ __forceinline__ unsigned pk2(float lo, float hi) { f32x2_t v = {lo, hi}; bf16x2_t b = __builtin_convertvector(v, bf16x2_t); return __builtin_bit_cast(unsigned, b); }
; __device__ __forceinline__ float bflo(unsigned u) { return __uint_as_float(u << 16); }
; __device__ __forceinline__ float bfhi(unsigned u) { return __uint_as_float(u & 0xffff0000u); }
; __device__ __forceinline__ void hgrn_scan_phase(const Args& a) {
;     ...
;         const f32x4* dc = (const f32x4*)((const float*)(a.ws + WS_DECAY) + (size_t)bh * 32 * 128 + dkc * 4);
;         float r0 = 0.f, r1 = 0.f, r2 = 0.f, r3 = 0.f;
; #pragma unroll 8
;         for (int c = 0; c < 32; ++c) {
;             const u32x2 u = st[(size_t)c * 4096]; const f32x4 dd = dc[c * 32];
;             u32x2 o; o.x = pk2(r0, r1); o.y = pk2(r2, r3); st[(size_t)c * 4096] = o;
;             r0 = dd.x * r0 + bflo(u.x); r1 = dd.y * r1 + bfhi(u.x); r2 = dd.z * r2 + bflo(u.y); r3 = dd.w * r3 + bfhi(u.y);
;         }
	v_lshlrev_b32_e32 v212, 16, v164
	v_and_b32_e32 v213, 0xffff0000, v164
	v_lshlrev_b32_e32 v214, 16, v165
	v_and_b32_e32 v215, 0xffff0000, v165
	s_waitcnt vmcnt(51)
	v_pk_fma_f32 v[208:209], v[208:209], v[60:61], v[212:213]
	v_pk_fma_f32 v[210:211], v[210:211], v[62:63], v[214:215]
	v_cvt_pk_bf16_f32 v218, v208, v209
	v_cvt_pk_bf16_f32 v219, v210, v211
	global_store_dwordx2 v220, v[218:219], s[14:15]
	s_add_u32 s14, s14, 0x8000
	s_addc_u32 s15, s15, 0
	s_waitcnt vmcnt(51)
	v_lshlrev_b32_e32 v212, 16, v166
	v_and_b32_e32 v213, 0xffff0000, v166
	v_lshlrev_b32_e32 v214, 16, v167
	v_and_b32_e32 v215, 0xffff0000, v167
	s_waitcnt vmcnt(50)
	v_pk_fma_f32 v[208:209], v[208:209], v[64:65], v[212:213]
	v_pk_fma_f32 v[210:211], v[210:211], v[66:67], v[214:215]
	v_cvt_pk_bf16_f32 v216, v208, v209
	v_cvt_pk_bf16_f32 v217, v210, v211
	global_store_dwordx2 v220, v[216:217], s[14:15]
	s_add_u32 s14, s14, 0x8000
	s_addc_u32 s15, s15, 0
	s_waitcnt vmcnt(50)
	v_lshlrev_b32_e32 v212, 16, v168
	v_and_b32_e32 v213, 0xffff0000, v168
	v_lshlrev_b32_e32 v214, 16, v169
	v_and_b32_e32 v215, 0xffff0000, v169
	s_waitcnt vmcnt(49)
	v_pk_fma_f32 v[208:209], v[208:209], v[68:69], v[212:213]
	v_pk_fma_f32 v[210:211], v[210:211], v[70:71], v[214:215]
	v_cvt_pk_bf16_f32 v218, v208, v209
	v_cvt_pk_bf16_f32 v219, v210, v211
	global_store_dwordx2 v220, v[218:219], s[14:15]
	s_add_u32 s14, s14, 0x8000
	s_addc_u32 s15, s15, 0
	s_waitcnt vmcnt(49)
	v_lshlrev_b32_e32 v212, 16, v170
	v_and_b32_e32 v213, 0xffff0000, v170
	v_lshlrev_b32_e32 v214, 16, v171
	v_and_b32_e32 v215, 0xffff0000, v171
	s_waitcnt vmcnt(48)
	v_pk_fma_f32 v[208:209], v[208:209], v[72:73], v[212:213]
	v_pk_fma_f32 v[210:211], v[210:211], v[74:75], v[214:215]
	v_cvt_pk_bf16_f32 v216, v208, v209
	v_cvt_pk_bf16_f32 v217, v210, v211
	global_store_dwordx2 v220, v[216:217], s[14:15]
	s_add_u32 s14, s14, 0x8000
	s_addc_u32 s15, s15, 0
	s_waitcnt vmcnt(48)
	v_lshlrev_b32_e32 v212, 16, v172
	v_and_b32_e32 v213, 0xffff0000, v172
	v_lshlrev_b32_e32 v214, 16, v173
	v_and_b32_e32 v215, 0xffff0000, v173
	s_waitcnt vmcnt(47)
	v_pk_fma_f32 v[208:209], v[208:209], v[76:77], v[212:213]
	v_pk_fma_f32 v[210:211], v[210:211], v[78:79], v[214:215]
	v_cvt_pk_bf16_f32 v218, v208, v209
	v_cvt_pk_bf16_f32 v219, v210, v211
	global_store_dwordx2 v220, v[218:219], s[14:15]
	s_add_u32 s14, s14, 0x8000
	s_addc_u32 s15, s15, 0
	s_waitcnt vmcnt(47)
	v_lshlrev_b32_e32 v212, 16, v174
	v_and_b32_e32 v213, 0xffff0000, v174
	v_lshlrev_b32_e32 v214, 16, v175
	v_and_b32_e32 v215, 0xffff0000, v175
	s_waitcnt vmcnt(46)
	v_pk_fma_f32 v[208:209], v[208:209], v[84:85], v[212:213]
	v_pk_fma_f32 v[210:211], v[210:211], v[86:87], v[214:215]
	v_cvt_pk_bf16_f32 v216, v208, v209
	v_cvt_pk_bf16_f32 v217, v210, v211
	global_store_dwordx2 v220, v[216:217], s[14:15]
	s_add_u32 s14, s14, 0x8000
	s_addc_u32 s15, s15, 0
	s_waitcnt vmcnt(46)
	v_lshlrev_b32_e32 v212, 16, v196
	v_and_b32_e32 v213, 0xffff0000, v196
	v_lshlrev_b32_e32 v214, 16, v197
	v_and_b32_e32 v215, 0xffff0000, v197
	s_waitcnt vmcnt(45)
	v_pk_fma_f32 v[208:209], v[208:209], v[88:89], v[212:213]
	v_pk_fma_f32 v[210:211], v[210:211], v[90:91], v[214:215]
	v_cvt_pk_bf16_f32 v218, v208, v209
	v_cvt_pk_bf16_f32 v219, v210, v211
	global_store_dwordx2 v220, v[218:219], s[14:15]
	s_add_u32 s14, s14, 0x8000
	s_addc_u32 s15, s15, 0
	s_waitcnt vmcnt(45)
	v_lshlrev_b32_e32 v212, 16, v198
	v_and_b32_e32 v213, 0xffff0000, v198
	v_lshlrev_b32_e32 v214, 16, v199
	v_and_b32_e32 v215, 0xffff0000, v199
	s_waitcnt vmcnt(44)
	v_pk_fma_f32 v[208:209], v[208:209], v[92:93], v[212:213]
	v_pk_fma_f32 v[210:211], v[210:211], v[94:95], v[214:215]
	v_cvt_pk_bf16_f32 v216, v208, v209
	v_cvt_pk_bf16_f32 v217, v210, v211
	global_store_dwordx2 v220, v[216:217], s[14:15]
	s_add_u32 s14, s14, 0x8000
	s_addc_u32 s15, s15, 0
	s_waitcnt vmcnt(44)
	v_lshlrev_b32_e32 v212, 16, v200
	v_and_b32_e32 v213, 0xffff0000, v200
	v_lshlrev_b32_e32 v214, 16, v201
	v_and_b32_e32 v215, 0xffff0000, v201
	s_waitcnt vmcnt(43)
	v_pk_fma_f32 v[208:209], v[208:209], v[100:101], v[212:213]
	v_pk_fma_f32 v[210:211], v[210:211], v[102:103], v[214:215]
	v_cvt_pk_bf16_f32 v218, v208, v209
	v_cvt_pk_bf16_f32 v219, v210, v211
	global_store_dwordx2 v220, v[218:219], s[14:15]
	s_add_u32 s14, s14, 0x8000
	s_addc_u32 s15, s15, 0
	s_waitcnt vmcnt(43)
	v_lshlrev_b32_e32 v212, 16, v202
	v_and_b32_e32 v213, 0xffff0000, v202
	v_lshlrev_b32_e32 v214, 16, v203
	v_and_b32_e32 v215, 0xffff0000, v203
	s_waitcnt vmcnt(42)
	v_pk_fma_f32 v[208:209], v[208:209], v[104:105], v[212:213]
	v_pk_fma_f32 v[210:211], v[210:211], v[106:107], v[214:215]
	v_cvt_pk_bf16_f32 v216, v208, v209
	v_cvt_pk_bf16_f32 v217, v210, v211
	global_store_dwordx2 v220, v[216:217], s[14:15]
	s_add_u32 s14, s14, 0x8000
	s_addc_u32 s15, s15, 0
	s_waitcnt vmcnt(42)
; __device__ __forceinline__ unsigned pk2(float lo, float hi) { f32x2_t v = {lo, hi}; bf16x2_t b = __builtin_convertvector(v, bf16x2_t); return __builtin_bit_cast(unsigned, b); }
; __device__ __forceinline__ float bflo(unsigned u) { return __uint_as_float(u << 16); }
; __device__ __forceinline__ float bfhi(unsigned u) { return __uint_as_float(u & 0xffff0000u); }
; __device__ __forceinline__ void hgrn_scan_phase(const Args& a) {
;     ...
;         const f32x4* dc = (const f32x4*)((const float*)(a.ws + WS_DECAY) + (size_t)bh * 32 * 128 + dkc * 4);
;         float r0 = 0.f, r1 = 0.f, r2 = 0.f, r3 = 0.f;
; #pragma unroll 8
;         for (int c = 0; c < 32; ++c) {
;             const u32x2 u = st[(size_t)c * 4096]; const f32x4 dd = dc[c * 32];
;             u32x2 o; o.x = pk2(r0, r1); o.y = pk2(r2, r3); st[(size_t)c * 4096] = o;
;             r0 = dd.x * r0 + bflo(u.x); r1 = dd.y * r1 + bfhi(u.x); r2 = dd.z * r2 + bflo(u.y); r3 = dd.w * r3 + bfhi(u.y);
;         }
	v_lshlrev_b32_e32 v212, 16, v204
	v_and_b32_e32 v213, 0xffff0000, v204
	v_lshlrev_b32_e32 v214, 16, v205
	v_and_b32_e32 v215, 0xffff0000, v205
	s_waitcnt vmcnt(41)
	v_pk_fma_f32 v[208:209], v[208:209], v[108:109], v[212:213]
	v_pk_fma_f32 v[210:211], v[210:211], v[110:111], v[214:215]
	v_cvt_pk_bf16_f32 v218, v208, v209
	v_cvt_pk_bf16_f32 v219, v210, v211
	global_store_dwordx2 v220, v[218:219], s[14:15]
	s_add_u32 s14, s14, 0x8000
	s_addc_u32 s15, s15, 0
	s_waitcnt vmcnt(41)
	v_lshlrev_b32_e32 v212, 16, v206
	v_and_b32_e32 v213, 0xffff0000, v206
	v_lshlrev_b32_e32 v214, 16, v207
	v_and_b32_e32 v215, 0xffff0000, v207
	s_waitcnt vmcnt(40)
	v_pk_fma_f32 v[208:209], v[208:209], v[112:113], v[212:213]
	v_pk_fma_f32 v[210:211], v[210:211], v[114:115], v[214:215]
	v_cvt_pk_bf16_f32 v216, v208, v209
	v_cvt_pk_bf16_f32 v217, v210, v211
	global_store_dwordx2 v220, v[216:217], s[14:15]
	s_add_u32 s14, s14, 0x8000
	s_addc_u32 s15, s15, 0
	s_waitcnt vmcnt(39)
	v_lshlrev_b32_e32 v212, 16, v128
	v_and_b32_e32 v213, 0xffff0000, v128
	v_lshlrev_b32_e32 v214, 16, v129
	v_and_b32_e32 v215, 0xffff0000, v129
	s_waitcnt vmcnt(38)
	v_pk_fma_f32 v[208:209], v[208:209], v[12:13], v[212:213]
	v_pk_fma_f32 v[210:211], v[210:211], v[14:15], v[214:215]
	v_cvt_pk_bf16_f32 v218, v208, v209
	v_cvt_pk_bf16_f32 v219, v210, v211
	global_store_dwordx2 v220, v[218:219], s[14:15]
	s_add_u32 s14, s14, 0x8000
	s_addc_u32 s15, s15, 0
	s_waitcnt vmcnt(37)
	v_lshlrev_b32_e32 v212, 16, v130
	v_and_b32_e32 v213, 0xffff0000, v130
	v_lshlrev_b32_e32 v214, 16, v131
	v_and_b32_e32 v215, 0xffff0000, v131
	s_waitcnt vmcnt(36)
	v_pk_fma_f32 v[208:209], v[208:209], v[16:17], v[212:213]
	v_pk_fma_f32 v[210:211], v[210:211], v[18:19], v[214:215]
	v_cvt_pk_bf16_f32 v216, v208, v209
	v_cvt_pk_bf16_f32 v217, v210, v211
	global_store_dwordx2 v220, v[216:217], s[14:15]
	s_add_u32 s14, s14, 0x8000
	s_addc_u32 s15, s15, 0
	s_waitcnt vmcnt(35)
	v_lshlrev_b32_e32 v212, 16, v132
	v_and_b32_e32 v213, 0xffff0000, v132
	v_lshlrev_b32_e32 v214, 16, v133
	v_and_b32_e32 v215, 0xffff0000, v133
	s_waitcnt vmcnt(34)
	v_pk_fma_f32 v[208:209], v[208:209], v[20:21], v[212:213]
	v_pk_fma_f32 v[210:211], v[210:211], v[22:23], v[214:215]
	v_cvt_pk_bf16_f32 v218, v208, v209
	v_cvt_pk_bf16_f32 v219, v210, v211
	global_store_dwordx2 v220, v[218:219], s[14:15]
	s_add_u32 s14, s14, 0x8000
	s_addc_u32 s15, s15, 0
	s_waitcnt vmcnt(33)
	v_lshlrev_b32_e32 v212, 16, v134
	v_and_b32_e32 v213, 0xffff0000, v134
	v_lshlrev_b32_e32 v214, 16, v135
	v_and_b32_e32 v215, 0xffff0000, v135
	s_waitcnt vmcnt(32)
	v_pk_fma_f32 v[208:209], v[208:209], v[24:25], v[212:213]
	v_pk_fma_f32 v[210:211], v[210:211], v[26:27], v[214:215]
	v_cvt_pk_bf16_f32 v216, v208, v209
	v_cvt_pk_bf16_f32 v217, v210, v211
	global_store_dwordx2 v220, v[216:217], s[14:15]
	s_add_u32 s14, s14, 0x8000
	s_addc_u32 s15, s15, 0
	s_waitcnt vmcnt(31)
	v_lshlrev_b32_e32 v212, 16, v136
	v_and_b32_e32 v213, 0xffff0000, v136
	v_lshlrev_b32_e32 v214, 16, v137
	v_and_b32_e32 v215, 0xffff0000, v137
	s_waitcnt vmcnt(30)
	v_pk_fma_f32 v[208:209], v[208:209], v[28:29], v[212:213]
	v_pk_fma_f32 v[210:211], v[210:211], v[30:31], v[214:215]
	v_cvt_pk_bf16_f32 v218, v208, v209
	v_cvt_pk_bf16_f32 v219, v210, v211
	global_store_dwordx2 v220, v[218:219], s[14:15]
	s_add_u32 s14, s14, 0x8000
	s_addc_u32 s15, s15, 0
	s_waitcnt vmcnt(29)
	v_lshlrev_b32_e32 v212, 16, v138
	v_and_b32_e32 v213, 0xffff0000, v138
	v_lshlrev_b32_e32 v214, 16, v139
	v_and_b32_e32 v215, 0xffff0000, v139
	s_waitcnt vmcnt(28)
	v_pk_fma_f32 v[208:209], v[208:209], v[32:33], v[212:213]
	v_pk_fma_f32 v[210:211], v[210:211], v[34:35], v[214:215]
	v_cvt_pk_bf16_f32 v216, v208, v209
	v_cvt_pk_bf16_f32 v217, v210, v211
	global_store_dwordx2 v220, v[216:217], s[14:15]
	s_add_u32 s14, s14, 0x8000
	s_addc_u32 s15, s15, 0
	s_waitcnt vmcnt(27)
	v_lshlrev_b32_e32 v212, 16, v140
	v_and_b32_e32 v213, 0xffff0000, v140
	v_lshlrev_b32_e32 v214, 16, v141
	v_and_b32_e32 v215, 0xffff0000, v141
	s_waitcnt vmcnt(26)
	v_pk_fma_f32 v[208:209], v[208:209], v[36:37], v[212:213]
	v_pk_fma_f32 v[210:211], v[210:211], v[38:39], v[214:215]
	v_cvt_pk_bf16_f32 v218, v208, v209
	v_cvt_pk_bf16_f32 v219, v210, v211
	global_store_dwordx2 v220, v[218:219], s[14:15]
	s_add_u32 s14, s14, 0x8000
	s_addc_u32 s15, s15, 0
	s_waitcnt vmcnt(25)
	v_lshlrev_b32_e32 v212, 16, v142
	v_and_b32_e32 v213, 0xffff0000, v142
	v_lshlrev_b32_e32 v214, 16, v143
	v_and_b32_e32 v215, 0xffff0000, v143
	s_waitcnt vmcnt(24)
	v_pk_fma_f32 v[208:209], v[208:209], v[40:41], v[212:213]
	v_pk_fma_f32 v[210:211], v[210:211], v[42:43], v[214:215]
	s_branch .LBB0_527
